# attention: waves 0-3 run at raised wave priority (s_setprio 2) so the two waves of a SIMD de-phase MFMA and softmax VALU segments
# baseline (speedup 1.0000x reference)
.LBB0_657:
	s_add_u32 s24, s82, 0xa800000
	s_addc_u32 s25, s83, 0
	s_add_u32 s28, s82, 0xc800000
	s_addc_u32 s33, s83, 0
	s_add_u32 s36, s82, 0xe800000
	v_cmp_gt_u32_e32 vcc, 32, v7
	s_addc_u32 s37, s83, 0
	s_add_u32 s38, s82, 0x10800000
	v_cndmask_b32_e32 v7, v9, v8, vcc
	v_add_f32_e32 v7, v7, v10
	s_addc_u32 s39, s83, 0
	v_sub_f32_e32 v8, v7, v5
	s_add_u32 s40, s82, 0x82a0000
	v_pk_add_f32 v[2:3], v[2:3], v[8:9] op_sel_hi:[1,0]
	v_pk_add_f32 v[4:5], v[4:5], v[8:9] op_sel_hi:[1,0]
	s_mov_b32 s4, 0x413504f3
	s_addc_u32 s41, s83, 0
	v_pk_mul_f32 v[4:5], v[4:5], s[4:5] op_sel_hi:[1,0]
	v_pk_mul_f32 v[2:3], v[2:3], s[4:5] op_sel_hi:[1,0]
	v_readlane_b32 s4, v253, 12
	v_readlane_b32 s5, v253, 13
	s_add_u32 s10, s40, s4
	s_addc_u32 s11, s41, s5
	v_readlane_b32 s4, v253, 14
	v_readlane_b32 s5, v253, 15
	s_add_u32 s8, s24, s4
	s_addc_u32 s9, s25, s5
	v_readlane_b32 s6, v253, 63
	v_readlane_b32 s7, v254, 0
	s_add_u32 s4, s28, s6
	s_addc_u32 s5, s33, s7
	s_add_u32 s6, s36, s6
	s_addc_u32 s7, s37, s7
	v_readlane_b32 s12, v253, 16
	s_add_u32 s12, s38, s12
	s_addc_u32 s13, s39, 0
	v_readlane_b32 s14, v253, 17
	v_lshl_add_u64 v[0:1], v[0:1], 2, s[10:11]
	v_readlane_b32 s15, v253, 18
	s_add_u32 s12, s12, s14
	global_store_dwordx4 v[0:1], v[2:5], off
	s_addc_u32 s13, s13, s15
	v_readlane_b32 s14, v254, 1
	v_mov_b32_e32 v7, v247
	s_waitcnt vmcnt(0)
	s_barrier
	s_add_u32 s22, s12, s14
	s_addc_u32 s23, s13, 0
	v_readfirstlane_b32 s12, v7
	s_ashr_i32 s12, s12, 1
	v_lshrrev_b32_e32 v2, 1, v7
	v_mov_b32_e32 v0, s12
	s_movk_i32 s12, 0xffe0
	v_bfi_b32 v0, s12, v0, v7
	v_ashrrev_i32_e32 v1, 31, v0
	v_lshlrev_b64 v[0:1], 8, v[0:1]
	v_lshl_add_u64 v[0:1], s[8:9], 0, v[0:1]
	v_and_b32_e32 v208, 16, v2
	v_lshl_add_u64 v[0:1], v[0:1], 0, v[208:209]
	v_ashrrev_i32_e32 v18, 4, v7
	v_readlane_b32 s12, v253, 20
	global_load_dwordx4 v[156:159], v[0:1], off
	global_load_dwordx4 v[152:155], v[0:1], off offset:32
	global_load_dwordx4 v[148:151], v[0:1], off offset:64
	global_load_dwordx4 v[144:147], v[0:1], off offset:96
	global_load_dwordx4 v[140:143], v[0:1], off offset:128
	global_load_dwordx4 v[136:139], v[0:1], off offset:160
	global_load_dwordx4 v[132:135], v[0:1], off offset:192
	global_load_dwordx4 v[128:131], v[0:1], off offset:224
	v_add_u32_e32 v0, s12, v18
	v_ashrrev_i32_e32 v1, 31, v0
	v_lshlrev_b64 v[0:1], 8, v[0:1]
	s_mov_b64 s[12:13], 0x2000
	v_lshlrev_b32_e32 v19, 4, v7
	v_lshl_add_u64 v[16:17], v[0:1], 0, s[12:13]
	v_lshlrev_b32_e32 v12, 2, v7
	v_and_b32_e32 v208, 0xf0, v19
	v_lshl_add_u64 v[4:5], s[6:7], 0, v[0:1]
	v_lshl_add_u64 v[0:1], s[4:5], 0, v[0:1]
	v_lshl_add_u64 v[2:3], s[4:5], 0, v[16:17]
	v_ashrrev_i32_e32 v13, 31, v12
	v_lshl_add_u64 v[0:1], v[0:1], 0, v[208:209]
	v_lshl_add_u64 v[8:9], v[2:3], 0, v[208:209]
	v_lshl_add_u64 v[12:13], v[12:13], 2, s[10:11]
	v_lshl_add_u64 v[4:5], v[4:5], 0, v[208:209]
	v_lshl_add_u64 v[16:17], s[6:7], 0, v[16:17]
	global_load_dwordx4 v[0:3], v[0:1], off
	s_nop 0
	global_load_dwordx4 v[8:11], v[8:9], off
	v_lshl_add_u64 v[16:17], v[16:17], 0, v[208:209]
	global_load_dwordx4 v[12:15], v[12:13], off
	s_nop 0
	global_load_dwordx4 v[100:103], v[4:5], off
	global_load_dwordx4 v[96:99], v[16:17], off
	v_xor_b32_e32 v4, 1, v250
	v_add_u32_e32 v5, 64, v6
	v_cmp_lt_i32_e32 vcc, v4, v5
	s_movk_i32 s12, 0xf0
	s_waitcnt vmcnt(0)
	v_readlane_b32 s34, v253, 19
	v_cndmask_b32_e32 v4, v250, v4, vcc
	v_lshlrev_b32_e32 v198, 2, v4
	v_and_b32_e32 v4, 0x70, v7
	v_lshlrev_b32_e32 v5, 8, v18
	v_bitop3_b32 v4, v19, v4, s12 bitop3:0x6c
	s_mov_b32 s42, 0
	v_readlane_b32 s43, v253, 60
	s_mov_b32 s44, s34
	v_add_u32_e32 v6, 0, v19
	v_add3_u32 v4, 0, v5, v4
	s_mov_b64 s[12:13], s[6:7]
	s_mov_b64 s[16:17], s[22:23]
	s_mov_b64 s[14:15], s[4:5]
	v_add_u32_e32 v5, 0x10800, v6
	s_waitcnt vmcnt(4)
	ds_write_b128 v4, v[0:3] offset:32768
	s_waitcnt vmcnt(3)
	ds_write_b128 v4, v[8:11] offset:40960
	s_waitcnt vmcnt(2)
	ds_write_b128 v5, v[12:15]
	v_readfirstlane_b32 vcc_lo, v247
	s_cmp_lt_u32 vcc_lo, 0x100
	s_cbranch_scc0 .Lattprio_skip
	s_setprio 2
.Lattprio_skip:
	s_waitcnt lgkmcnt(0)
	s_barrier
	s_branch .LBB0_659

.LBB0_822:
	s_setprio 0
	s_mov_b64 s[4:5], 0
